# decode unit prologue de-serialised: four masked Q fragment load pairs and the page-table load issued together (nine loads, counted waits) instead of five dependent round trips
# speedup vs baseline: 1.0499x; 1.0499x over previous
.LBB0_420:
	s_ashr_i32 s35, s30, 3
	s_lshl_b32 s4, s35, 2
	v_and_or_b32 v0, v188, 3, s4
	v_ashrrev_i32_e32 v1, 31, v0
	v_lshlrev_b64 v[0:1], 11, v[0:1]
	v_bfe_u32 v13, v188, 2, 2
	v_lshl_add_u64 v[0:1], s[18:19], 0, v[0:1]
	s_lshl_b32 s16, s24, 9
	v_bfe_u32 v189, v188, 4, 2
	v_lshl_add_u64 v[0:1], v[0:1], 0, s[16:17]
	v_lshlrev_b32_e32 v168, 8, v13
	v_and_b32_e32 v12, 15, v188
	v_lshl_add_u64 v[0:1], v[0:1], 0, v[168:169]
	v_lshlrev_b32_e32 v168, 5, v189
	v_lshl_add_u64 v[10:11], v[0:1], 0, v[168:169]
	v_cmp_gt_u32_e32 vcc, 4, v12
	v_mov_b32_e32 v0, 0
	v_mov_b32_e32 v2, 0
	v_mov_b32_e32 v3, 0
	v_mov_b32_e32 v4, 0
	v_mov_b32_e32 v5, 0
	v_mov_b32_e32 v6, 0
	v_mov_b32_e32 v7, 0
	v_mov_b32_e32 v8, 0
	v_mov_b32_e32 v9, 0
	v_mov_b32_e32 v112, 0
	v_mov_b32_e32 v113, 0
	v_mov_b32_e32 v114, 0
	v_mov_b32_e32 v115, 0
	v_mov_b32_e32 v116, 0
	v_mov_b32_e32 v117, 0
	v_mov_b32_e32 v118, 0
	v_mov_b32_e32 v119, 0
	v_mov_b32_e32 v120, 0
	v_mov_b32_e32 v121, 0
	v_mov_b32_e32 v122, 0
	v_mov_b32_e32 v123, 0
	v_mov_b32_e32 v124, 0
	v_mov_b32_e32 v125, 0
	v_mov_b32_e32 v126, 0
	v_mov_b32_e32 v127, 0
	v_mov_b32_e32 v128, 0
	v_mov_b32_e32 v129, 0
	v_mov_b32_e32 v130, 0
	v_mov_b32_e32 v131, 0
	v_mov_b32_e32 v132, 0
	v_mov_b32_e32 v133, 0
	v_mov_b32_e32 v134, 0
	v_mov_b32_e32 v135, 0
	s_and_saveexec_b64 s[4:5], vcc
	global_load_dwordx4 v[2:5], v[10:11], off
	global_load_dwordx4 v[6:9], v[10:11], off offset:16
	global_load_dwordx4 v[112:115], v[10:11], off offset:128
	global_load_dwordx4 v[116:119], v[10:11], off offset:144
	s_or_b64 exec, exec, s[4:5]
	v_cmp_gt_u32_e32 vcc, 8, v12
	v_cmp_eq_u32_e64 s[4:5], 1, v13
	s_and_b64 s[4:5], vcc, s[4:5]
	s_and_saveexec_b64 s[40:41], s[4:5]
	global_load_dwordx4 v[120:123], v[10:11], off
	global_load_dwordx4 v[124:127], v[10:11], off offset:16
	global_load_dwordx4 v[128:131], v[10:11], off offset:128
	global_load_dwordx4 v[132:135], v[10:11], off offset:144
	s_or_b64 exec, exec, s[40:41]
	s_lshl_b32 s16, s24, 7
	s_and_b32 s24, s30, 7
	s_lshl_b32 s4, s24, 3
	s_and_b32 s45, s31, -4
	s_add_i32 s45, s45, s4
	s_lshl_b32 s4, s35, 6
	s_add_i32 s4, s45, s4
	s_ashr_i32 s5, s4, 31
	s_lshl_b32 s25, s31, 10
	s_lshl_b64 s[4:5], s[4:5], 2
	s_add_u32 s4, s6, s4
	s_addc_u32 s5, s7, s5
	global_load_dwordx4 v[136:139], v169, s[4:5]
	s_waitcnt vmcnt(8)
	v_cvt_pk_bf16_f32 v24, v2, v3
	v_cvt_pk_bf16_f32 v25, v4, v5
	s_waitcnt vmcnt(7)
	v_cvt_pk_bf16_f32 v26, v6, v7
	v_cvt_pk_bf16_f32 v27, v8, v9
	s_waitcnt vmcnt(6)
	v_cvt_pk_bf16_f32 v48, v112, v113
	v_cvt_pk_bf16_f32 v49, v114, v115
	s_waitcnt vmcnt(5)
	v_cvt_pk_bf16_f32 v50, v116, v117
	v_cvt_pk_bf16_f32 v51, v118, v119
	s_waitcnt vmcnt(4)
	v_cvt_pk_bf16_f32 v52, v120, v121
	v_cvt_pk_bf16_f32 v53, v122, v123
	s_waitcnt vmcnt(3)
	v_cvt_pk_bf16_f32 v54, v124, v125
	v_cvt_pk_bf16_f32 v55, v126, v127
	s_waitcnt vmcnt(2)
	v_cvt_pk_bf16_f32 v60, v128, v129
	v_cvt_pk_bf16_f32 v61, v130, v131
	s_waitcnt vmcnt(1)
	v_cvt_pk_bf16_f32 v62, v132, v133
	v_cvt_pk_bf16_f32 v63, v134, v135
	v_and_b32_e32 v9, 63, v188
	v_and_b32_e32 v13, 31, v188
	v_lshrrev_b32_e32 v16, 5, v9
	v_lshlrev_b32_e32 v171, 2, v13
	v_lshlrev_b32_e32 v4, 9, v16
	v_or3_b32 v8, s16, v4, v171
	s_add_i32 s16, s25, 0
	v_lshlrev_b32_e32 v168, 2, v8
	v_mov_b32_e32 v174, 0
	s_mov_b32 s51, 0
	v_or_b32_e32 v179, 0xffffe000, v12
	v_mov_b32_e32 v184, v182
	v_mov_b32_e32 v185, v182
	v_mov_b32_e32 v172, 0xf149f2ca
	s_mov_b32 s53, 0
	v_mov_b32_e32 v175, v174
	v_mov_b32_e32 v176, v174
	v_mov_b32_e32 v177, v174
	v_mov_b32_e32 v178, 0xf149f2ca
	v_mov_b32_e32 v180, 0xf149f2ca
	v_mov_b32_e32 v170, 0xf149f2ca
	s_waitcnt vmcnt(0)
	v_mov_b32_e32 v0, v136
	v_mov_b32_e32 v1, v137
	v_mov_b32_e32 v2, v138
	v_mov_b32_e32 v3, v139
	v_readfirstlane_b32 s40, v0
	s_ashr_i32 s41, s40, 31
	s_lshl_b64 s[4:5], s[40:41], 18
	s_add_u32 s42, s8, s4
	s_addc_u32 s43, s9, s5
	v_lshl_add_u64 v[4:5], s[42:43], 0, v[168:169]
	v_add_co_u32_e32 v6, vcc, s13, v4
	s_add_u32 s4, s10, s4
	s_nop 0
	v_addc_co_u32_e32 v7, vcc, 0, v5, vcc
	v_add_co_u32_e32 v10, vcc, s14, v4
	s_addc_u32 s5, s11, s5
	s_nop 0
	v_addc_co_u32_e32 v11, vcc, 0, v5, vcc
	v_add_co_u32_e32 v14, vcc, s15, v4
	v_readfirstlane_b32 s41, v1
	s_nop 0
	v_addc_co_u32_e32 v15, vcc, 0, v5, vcc
	v_add_co_u32_e32 v4, vcc, s26, v4
	v_readfirstlane_b32 s47, v2
	s_nop 0
	v_addc_co_u32_e32 v5, vcc, 0, v5, vcc
	global_load_dwordx4 v[140:143], v[6:7], off offset:-4096 nt
	global_load_dwordx4 v[136:139], v[6:7], off nt
	global_load_dwordx4 v[132:135], v[10:11], off offset:-4096 nt
	global_load_dwordx4 v[128:131], v[10:11], off nt
	global_load_dwordx4 v[124:127], v[14:15], off offset:-4096 nt
	global_load_dwordx4 v[120:123], v[14:15], off nt
	global_load_dwordx4 v[116:119], v[4:5], off nt
	v_lshl_add_u64 v[4:5], s[4:5], 0, v[168:169]
	v_add_co_u32_e32 v6, vcc, s13, v4
	global_load_dwordx4 v[144:147], v168, s[42:43] nt
	global_load_dwordx4 v[72:75], v168, s[4:5] nt
	v_addc_co_u32_e32 v7, vcc, 0, v5, vcc
	v_add_co_u32_e32 v10, vcc, s14, v4
	s_mul_i32 s4, s31, 0x1100
	s_nop 0
	v_addc_co_u32_e32 v11, vcc, 0, v5, vcc
	v_add_co_u32_e32 v14, vcc, s15, v4
	s_add_i32 s25, s4, 0
	s_nop 0
	v_addc_co_u32_e32 v15, vcc, 0, v5, vcc
	v_add_co_u32_e32 v4, vcc, s26, v4
	v_mov_b32_e32 v0, s25
	s_nop 0
	v_addc_co_u32_e32 v5, vcc, 0, v5, vcc
	global_load_dwordx4 v[80:83], v[6:7], off offset:-4096 nt
	global_load_dwordx4 v[76:79], v[6:7], off nt
	global_load_dwordx4 v[88:91], v[10:11], off offset:-4096 nt
	global_load_dwordx4 v[84:87], v[10:11], off nt
	global_load_dwordx4 v[96:99], v[14:15], off offset:-4096 nt
	global_load_dwordx4 v[92:95], v[14:15], off nt
	global_load_dwordx4 v[104:107], v[4:5], off nt
	v_lshl_add_u32 v1, v13, 3, s25
	v_cmp_gt_u32_e32 vcc, 32, v9
	v_and_b32_e32 v9, 32, v188
	v_mul_u32_u24_e32 v10, 0x110, v16
	v_mov_b32_e32 v6, v169
	v_mov_b32_e32 v7, v169
	v_readfirstlane_b32 s49, v3
	v_mad_u32_u24 v0, v12, s27, v0
	v_and_b32_e32 v2, 48, v188
	v_lshl_add_u32 v3, v12, 5, s16
	v_mov_b32_e32 v4, v169
	v_mov_b32_e32 v5, v169
	v_lshlrev_b32_e32 v168, 2, v8
	v_add_u32_e32 v181, v1, v10
	v_add_u32_e32 v173, s16, v9
	v_mov_b64_e32 v[18:19], v[6:7]
	v_mov_b64_e32 v[30:31], v[6:7]
	v_mov_b64_e32 v[38:39], v[6:7]
	v_mov_b64_e32 v[10:11], v[6:7]
	v_mov_b64_e32 v[22:23], v[6:7]
	v_mov_b64_e32 v[34:35], v[6:7]
	v_mov_b64_e32 v[46:47], v[6:7]
	v_add_u32_e32 v190, v0, v2
	v_add_u32_e32 v191, v3, v2
	v_mov_b64_e32 v[16:17], v[4:5]
	v_mov_b64_e32 v[28:29], v[4:5]
	v_mov_b64_e32 v[36:37], v[4:5]
	v_mov_b64_e32 v[8:9], v[4:5]
	v_mov_b64_e32 v[20:21], v[4:5]
	v_mov_b64_e32 v[32:33], v[4:5]
	v_mov_b64_e32 v[44:45], v[4:5]

.LBB0_557:
	s_ashr_i32 s43, s31, 3
	s_lshl_b32 s6, s43, 2
	v_and_or_b32 v0, v188, 3, s6
	v_ashrrev_i32_e32 v1, 31, v0
	v_lshlrev_b64 v[0:1], 11, v[0:1]
	v_bfe_u32 v13, v188, 2, 2
	v_lshl_add_u64 v[0:1], s[18:19], 0, v[0:1]
	s_lshl_b32 s16, s24, 9
	v_bfe_u32 v189, v188, 4, 2
	v_lshl_add_u64 v[0:1], v[0:1], 0, s[16:17]
	v_lshlrev_b32_e32 v168, 8, v13
	v_and_b32_e32 v12, 15, v188
	v_lshl_add_u64 v[0:1], v[0:1], 0, v[168:169]
	v_lshlrev_b32_e32 v168, 5, v189
	v_lshl_add_u64 v[10:11], v[0:1], 0, v[168:169]
	v_cmp_gt_u32_e32 vcc, 4, v12
	v_mov_b32_e32 v0, 0
	v_mov_b32_e32 v2, 0
	v_mov_b32_e32 v3, 0
	v_mov_b32_e32 v4, 0
	v_mov_b32_e32 v5, 0
	v_mov_b32_e32 v6, 0
	v_mov_b32_e32 v7, 0
	v_mov_b32_e32 v8, 0
	v_mov_b32_e32 v9, 0
	v_mov_b32_e32 v112, 0
	v_mov_b32_e32 v113, 0
	v_mov_b32_e32 v114, 0
	v_mov_b32_e32 v115, 0
	v_mov_b32_e32 v116, 0
	v_mov_b32_e32 v117, 0
	v_mov_b32_e32 v118, 0
	v_mov_b32_e32 v119, 0
	v_mov_b32_e32 v120, 0
	v_mov_b32_e32 v121, 0
	v_mov_b32_e32 v122, 0
	v_mov_b32_e32 v123, 0
	v_mov_b32_e32 v124, 0
	v_mov_b32_e32 v125, 0
	v_mov_b32_e32 v126, 0
	v_mov_b32_e32 v127, 0
	v_mov_b32_e32 v128, 0
	v_mov_b32_e32 v129, 0
	v_mov_b32_e32 v130, 0
	v_mov_b32_e32 v131, 0
	v_mov_b32_e32 v132, 0
	v_mov_b32_e32 v133, 0
	v_mov_b32_e32 v134, 0
	v_mov_b32_e32 v135, 0
	s_and_saveexec_b64 s[6:7], vcc
	global_load_dwordx4 v[2:5], v[10:11], off
	global_load_dwordx4 v[6:9], v[10:11], off offset:16
	global_load_dwordx4 v[112:115], v[10:11], off offset:128
	global_load_dwordx4 v[116:119], v[10:11], off offset:144
	s_or_b64 exec, exec, s[6:7]
	v_cmp_gt_u32_e32 vcc, 8, v12
	v_cmp_eq_u32_e64 s[6:7], 1, v13
	s_and_b64 s[6:7], vcc, s[6:7]
	s_and_saveexec_b64 s[22:23], s[6:7]
	global_load_dwordx4 v[120:123], v[10:11], off
	global_load_dwordx4 v[124:127], v[10:11], off offset:16
	global_load_dwordx4 v[128:131], v[10:11], off offset:128
	global_load_dwordx4 v[132:135], v[10:11], off offset:144
	s_or_b64 exec, exec, s[22:23]
	s_lshl_b32 s16, s24, 7
	s_and_b32 s24, s31, 7
	s_lshl_b32 s6, s24, 3
	s_and_b32 s25, s35, -4
	s_add_i32 s25, s25, s6
	s_lshl_b32 s6, s43, 6
	s_add_i32 s6, s25, s6
	s_ashr_i32 s7, s6, 31
	s_lshl_b32 s22, s35, 10
	s_lshl_b64 s[6:7], s[6:7], 2
	s_add_u32 s6, s12, s6
	s_addc_u32 s7, s13, s7
	global_load_dwordx4 v[136:139], v169, s[6:7]
	s_waitcnt vmcnt(8)
	v_cvt_pk_bf16_f32 v24, v2, v3
	v_cvt_pk_bf16_f32 v25, v4, v5
	s_waitcnt vmcnt(7)
	v_cvt_pk_bf16_f32 v26, v6, v7
	v_cvt_pk_bf16_f32 v27, v8, v9
	s_waitcnt vmcnt(6)
	v_cvt_pk_bf16_f32 v48, v112, v113
	v_cvt_pk_bf16_f32 v49, v114, v115
	s_waitcnt vmcnt(5)
	v_cvt_pk_bf16_f32 v50, v116, v117
	v_cvt_pk_bf16_f32 v51, v118, v119
	s_waitcnt vmcnt(4)
	v_cvt_pk_bf16_f32 v52, v120, v121
	v_cvt_pk_bf16_f32 v53, v122, v123
	s_waitcnt vmcnt(3)
	v_cvt_pk_bf16_f32 v54, v124, v125
	v_cvt_pk_bf16_f32 v55, v126, v127
	s_waitcnt vmcnt(2)
	v_cvt_pk_bf16_f32 v60, v128, v129
	v_cvt_pk_bf16_f32 v61, v130, v131
	s_waitcnt vmcnt(1)
	v_cvt_pk_bf16_f32 v62, v132, v133
	v_cvt_pk_bf16_f32 v63, v134, v135
	v_and_b32_e32 v9, 63, v188
	v_and_b32_e32 v13, 31, v188
	v_lshrrev_b32_e32 v16, 5, v9
	v_lshlrev_b32_e32 v171, 2, v13
	v_lshlrev_b32_e32 v4, 9, v16
	v_or3_b32 v8, s16, v4, v171
	s_add_i32 s16, s22, 0
	v_lshlrev_b32_e32 v168, 2, v8
	v_mov_b32_e32 v174, 0
	s_mov_b32 s51, 0
	v_or_b32_e32 v179, 0xffffe000, v12
	v_mov_b32_e32 v184, v182
	v_mov_b32_e32 v185, v182
	v_mov_b32_e32 v172, 0xf149f2ca
	s_mov_b32 s53, 0
	v_mov_b32_e32 v175, v174
	v_mov_b32_e32 v176, v174
	v_mov_b32_e32 v177, v174
	v_mov_b32_e32 v178, 0xf149f2ca
	v_mov_b32_e32 v180, 0xf149f2ca
	v_mov_b32_e32 v170, 0xf149f2ca
	s_waitcnt vmcnt(0)
	v_mov_b32_e32 v0, v136
	v_mov_b32_e32 v1, v137
	v_mov_b32_e32 v2, v138
	v_mov_b32_e32 v3, v139
	v_readfirstlane_b32 s22, v0
	s_ashr_i32 s23, s22, 31
	s_lshl_b64 s[6:7], s[22:23], 18
	s_add_u32 s40, s8, s6
	s_addc_u32 s41, s9, s7
	v_lshl_add_u64 v[4:5], s[40:41], 0, v[168:169]
	v_add_co_u32_e32 v6, vcc, s14, v4
	s_add_u32 s6, s10, s6
	s_nop 0
	v_addc_co_u32_e32 v7, vcc, 0, v5, vcc
	v_add_co_u32_e32 v10, vcc, s15, v4
	s_addc_u32 s7, s11, s7
	s_nop 0
	v_addc_co_u32_e32 v11, vcc, 0, v5, vcc
	v_add_co_u32_e32 v14, vcc, s26, v4
	v_readfirstlane_b32 s45, v1
	s_nop 0
	v_addc_co_u32_e32 v15, vcc, 0, v5, vcc
	v_add_co_u32_e32 v4, vcc, s27, v4
	v_readfirstlane_b32 s47, v2
	s_nop 0
	v_addc_co_u32_e32 v5, vcc, 0, v5, vcc
	global_load_dwordx4 v[140:143], v[6:7], off offset:-4096 nt
	global_load_dwordx4 v[136:139], v[6:7], off nt
	global_load_dwordx4 v[132:135], v[10:11], off offset:-4096 nt
	global_load_dwordx4 v[128:131], v[10:11], off nt
	global_load_dwordx4 v[124:127], v[14:15], off offset:-4096 nt
	global_load_dwordx4 v[120:123], v[14:15], off nt
	global_load_dwordx4 v[116:119], v[4:5], off nt
	v_lshl_add_u64 v[4:5], s[6:7], 0, v[168:169]
	v_add_co_u32_e32 v6, vcc, s14, v4
	global_load_dwordx4 v[144:147], v168, s[40:41] nt
	global_load_dwordx4 v[72:75], v168, s[6:7] nt
	v_addc_co_u32_e32 v7, vcc, 0, v5, vcc
	v_add_co_u32_e32 v10, vcc, s15, v4
	s_mul_i32 s6, s35, 0x1100
	s_nop 0
	v_addc_co_u32_e32 v11, vcc, 0, v5, vcc
	v_add_co_u32_e32 v14, vcc, s26, v4
	s_add_i32 s23, s6, 0
	s_nop 0
	v_addc_co_u32_e32 v15, vcc, 0, v5, vcc
	v_add_co_u32_e32 v4, vcc, s27, v4
	v_mov_b32_e32 v0, s23
	s_nop 0
	v_addc_co_u32_e32 v5, vcc, 0, v5, vcc
	global_load_dwordx4 v[80:83], v[6:7], off offset:-4096 nt
	global_load_dwordx4 v[76:79], v[6:7], off nt
	global_load_dwordx4 v[88:91], v[10:11], off offset:-4096 nt
	global_load_dwordx4 v[84:87], v[10:11], off nt
	global_load_dwordx4 v[96:99], v[14:15], off offset:-4096 nt
	global_load_dwordx4 v[92:95], v[14:15], off nt
	global_load_dwordx4 v[104:107], v[4:5], off nt
	v_lshl_add_u32 v1, v13, 3, s23
	v_cmp_gt_u32_e32 vcc, 32, v9
	v_and_b32_e32 v9, 32, v188
	v_mul_u32_u24_e32 v10, 0x110, v16
	v_mov_b32_e32 v6, v169
	v_mov_b32_e32 v7, v169
	v_readfirstlane_b32 s49, v3
	v_mad_u32_u24 v0, v12, s28, v0
	v_and_b32_e32 v2, 48, v188
	v_lshl_add_u32 v3, v12, 5, s16
	v_mov_b32_e32 v4, v169
	v_mov_b32_e32 v5, v169
	v_lshlrev_b32_e32 v168, 2, v8
	v_add_u32_e32 v181, v1, v10
	v_add_u32_e32 v173, s16, v9
	v_mov_b64_e32 v[18:19], v[6:7]
	v_mov_b64_e32 v[30:31], v[6:7]
	v_mov_b64_e32 v[38:39], v[6:7]
	v_mov_b64_e32 v[10:11], v[6:7]
	v_mov_b64_e32 v[22:23], v[6:7]
	v_mov_b64_e32 v[34:35], v[6:7]
	v_mov_b64_e32 v[46:47], v[6:7]
	v_add_u32_e32 v190, v0, v2
	v_add_u32_e32 v191, v3, v2
	v_mov_b64_e32 v[16:17], v[4:5]
	v_mov_b64_e32 v[28:29], v[4:5]
	v_mov_b64_e32 v[36:37], v[4:5]
	v_mov_b64_e32 v[8:9], v[4:5]
	v_mov_b64_e32 v[20:21], v[4:5]
	v_mov_b64_e32 v[32:33], v[4:5]
	v_mov_b64_e32 v[44:45], v[4:5]
